# v51 + SGPR-base LDS-DMA addressing in the two tiled-operand K-loops (30 64-bit VALU adds removed per loop pair)
# speedup vs baseline: 1.0058x; 1.0005x over previous
.LBB0_228:
	ds_read_b128 v[140:143], v219
	ds_read_b128 v[144:147], v219 offset:1024
	ds_read_b128 v[148:151], v219 offset:2048
	ds_read_b128 v[152:155], v219 offset:3072
	ds_read_b128 v[156:159], v221
	ds_read_b128 v[164:167], v221 offset:1024
	ds_read_b128 v[168:171], v221 offset:2048
	ds_read_b128 v[172:175], v221 offset:3072
	s_add_i32 s62, s26, 2
	s_add_u32 s27, s24, 0x4000
	s_addc_u32 s28, s25, 0
	s_cmp_eq_u32 s46, s26
	s_cselect_b32 s30, s0, s27
	s_cselect_b32 s31, s1, s28
	s_cselect_b32 s28, s22, s60
	s_cselect_b32 s29, s23, s61
	s_add_u32 s26, s30, 0x8000
	s_addc_u32 s27, s31, 0
	s_add_i32 m0, s38, 0xc000
	ds_read_b128 v[176:179], v222
	ds_read_b128 v[180:183], v222 offset:1024
	ds_read_b128 v[184:187], v222 offset:2048
	ds_read_b128 v[188:191], v222 offset:3072
	ds_read_b128 v[192:195], v222 offset:4096
	ds_read_b128 v[196:199], v222 offset:5120
	ds_read_b128 v[200:203], v222 offset:6144
	ds_read_b128 v[204:207], v222 offset:7168
	global_load_lds_dwordx4 v132, s[24:25]
	s_add_i32 m0, s38, 0xe000
	s_nop 0
	global_load_lds_dwordx4 v134, s[24:25]
	s_waitcnt vmcnt(8)
	s_waitcnt lgkmcnt(0)
	s_barrier
	s_waitcnt lgkmcnt(0)
	v_mfma_f32_16x16x32_bf16 v[124:127], v[140:143], v[176:179], v[124:127]
	v_mfma_f32_16x16x32_bf16 v[124:127], v[144:147], v[180:183], v[124:127]
	v_mfma_f32_16x16x32_bf16 v[120:123], v[152:155], v[180:183], v[120:123]
	v_mfma_f32_16x16x32_bf16 v[120:123], v[148:151], v[176:179], v[120:123]
	v_mfma_f32_16x16x32_bf16 v[108:111], v[156:159], v[176:179], v[108:111]
	v_mfma_f32_16x16x32_bf16 v[108:111], v[164:167], v[180:183], v[108:111]
	v_mfma_f32_16x16x32_bf16 v[100:103], v[172:175], v[180:183], v[100:103]
	v_mfma_f32_16x16x32_bf16 v[100:103], v[168:171], v[176:179], v[100:103]
	v_mfma_f32_16x16x32_bf16 v[84:87], v[168:171], v[184:187], v[84:87]
	v_mfma_f32_16x16x32_bf16 v[84:87], v[172:175], v[188:191], v[84:87]
	v_mfma_f32_16x16x32_bf16 v[92:95], v[164:167], v[188:191], v[92:95]
	v_mfma_f32_16x16x32_bf16 v[92:95], v[156:159], v[184:187], v[92:95]
	v_mfma_f32_16x16x32_bf16 v[112:115], v[148:151], v[184:187], v[112:115]
	v_mfma_f32_16x16x32_bf16 v[112:115], v[152:155], v[188:191], v[112:115]
	v_mfma_f32_16x16x32_bf16 v[116:119], v[144:147], v[188:191], v[116:119]
	v_mfma_f32_16x16x32_bf16 v[116:119], v[140:143], v[184:187], v[116:119]
	v_mfma_f32_16x16x32_bf16 v[104:107], v[140:143], v[192:195], v[104:107]
	v_mfma_f32_16x16x32_bf16 v[104:107], v[144:147], v[196:199], v[104:107]
	v_mfma_f32_16x16x32_bf16 v[96:99], v[152:155], v[196:199], v[96:99]
	v_mfma_f32_16x16x32_bf16 v[96:99], v[148:151], v[192:195], v[96:99]
	v_mfma_f32_16x16x32_bf16 v[76:79], v[156:159], v[192:195], v[76:79]
	v_mfma_f32_16x16x32_bf16 v[76:79], v[164:167], v[196:199], v[76:79]
	v_mfma_f32_16x16x32_bf16 v[72:75], v[172:175], v[196:199], v[72:75]
	v_mfma_f32_16x16x32_bf16 v[72:75], v[168:171], v[192:195], v[72:75]
	v_mfma_f32_16x16x32_bf16 v[64:67], v[168:171], v[200:203], v[64:67]
	v_mfma_f32_16x16x32_bf16 v[64:67], v[172:175], v[204:207], v[64:67]
	v_mfma_f32_16x16x32_bf16 v[68:71], v[164:167], v[204:207], v[68:71]
	v_mfma_f32_16x16x32_bf16 v[68:71], v[156:159], v[200:203], v[68:71]
	v_mfma_f32_16x16x32_bf16 v[80:83], v[148:151], v[200:203], v[80:83]
	v_mfma_f32_16x16x32_bf16 v[80:83], v[152:155], v[204:207], v[80:83]
	v_mfma_f32_16x16x32_bf16 v[88:91], v[144:147], v[204:207], v[88:91]
	v_mfma_f32_16x16x32_bf16 v[88:91], v[140:143], v[200:203], v[88:91]
	s_barrier
	s_add_i32 s63, s50, s37
	s_mov_b32 m0, s63
	ds_read_b128 v[176:179], v222 offset:16384
	ds_read_b128 v[180:183], v222 offset:17408
	ds_read_b128 v[184:187], v222 offset:18432
	ds_read_b128 v[188:191], v222 offset:19456
	ds_read_b128 v[192:195], v222 offset:20480
	ds_read_b128 v[196:199], v222 offset:21504
	ds_read_b128 v[200:203], v222 offset:22528
	ds_read_b128 v[204:207], v222 offset:23552
	global_load_lds_dwordx4 v128, s[28:29]
	s_add_i32 m0, s63, 0x2000
	s_add_u32 s64, s28, 0x4000
	s_addc_u32 s65, s29, 0
	s_add_i32 s63, s51, s37
	global_load_lds_dwordx4 v130, s[28:29]
	s_mov_b32 m0, s63
	s_nop 0
	global_load_lds_dwordx4 v128, s[64:65]
	s_add_i32 m0, s63, 0x2000
	s_nop 0
	global_load_lds_dwordx4 v130, s[64:65]
	s_mov_b32 m0, s38
	s_nop 0
	global_load_lds_dwordx4 v128, s[30:31]
	s_mov_b32 m0, s39
	s_nop 0
	global_load_lds_dwordx4 v130, s[30:31]
	s_waitcnt vmcnt(8)
	s_waitcnt lgkmcnt(0)
	s_barrier
	s_waitcnt lgkmcnt(0)
	v_mfma_f32_16x16x32_bf16 v[60:63], v[140:143], v[176:179], v[60:63]
	v_mfma_f32_16x16x32_bf16 v[60:63], v[144:147], v[180:183], v[60:63]
	v_mfma_f32_16x16x32_bf16 v[56:59], v[152:155], v[180:183], v[56:59]
	v_mfma_f32_16x16x32_bf16 v[56:59], v[148:151], v[176:179], v[56:59]
	v_mfma_f32_16x16x32_bf16 v[44:47], v[156:159], v[176:179], v[44:47]
	v_mfma_f32_16x16x32_bf16 v[44:47], v[164:167], v[180:183], v[44:47]
	v_mfma_f32_16x16x32_bf16 v[36:39], v[172:175], v[180:183], v[36:39]
	v_mfma_f32_16x16x32_bf16 v[36:39], v[168:171], v[176:179], v[36:39]
	v_mfma_f32_16x16x32_bf16 v[20:23], v[168:171], v[184:187], v[20:23]
	v_mfma_f32_16x16x32_bf16 v[20:23], v[172:175], v[188:191], v[20:23]
	v_mfma_f32_16x16x32_bf16 v[28:31], v[164:167], v[188:191], v[28:31]
	v_mfma_f32_16x16x32_bf16 v[28:31], v[156:159], v[184:187], v[28:31]
	v_mfma_f32_16x16x32_bf16 v[48:51], v[148:151], v[184:187], v[48:51]
	v_mfma_f32_16x16x32_bf16 v[48:51], v[152:155], v[188:191], v[48:51]
	v_mfma_f32_16x16x32_bf16 v[52:55], v[144:147], v[188:191], v[52:55]
	v_mfma_f32_16x16x32_bf16 v[52:55], v[140:143], v[184:187], v[52:55]
	v_mfma_f32_16x16x32_bf16 v[40:43], v[140:143], v[192:195], v[40:43]
	v_mfma_f32_16x16x32_bf16 v[40:43], v[144:147], v[196:199], v[40:43]
	v_mfma_f32_16x16x32_bf16 v[32:35], v[152:155], v[196:199], v[32:35]
	v_mfma_f32_16x16x32_bf16 v[32:35], v[148:151], v[192:195], v[32:35]
	v_mfma_f32_16x16x32_bf16 v[12:15], v[156:159], v[192:195], v[12:15]
	v_mfma_f32_16x16x32_bf16 v[12:15], v[164:167], v[196:199], v[12:15]
	v_mfma_f32_16x16x32_bf16 v[8:11], v[172:175], v[196:199], v[8:11]
	v_mfma_f32_16x16x32_bf16 v[8:11], v[168:171], v[192:195], v[8:11]
	v_mfma_f32_16x16x32_bf16 v[0:3], v[168:171], v[200:203], v[0:3]
	v_mfma_f32_16x16x32_bf16 v[0:3], v[172:175], v[204:207], v[0:3]
	v_mfma_f32_16x16x32_bf16 v[4:7], v[164:167], v[204:207], v[4:7]
	v_mfma_f32_16x16x32_bf16 v[4:7], v[156:159], v[200:203], v[4:7]
	v_mfma_f32_16x16x32_bf16 v[16:19], v[148:151], v[200:203], v[16:19]
	v_mfma_f32_16x16x32_bf16 v[16:19], v[152:155], v[204:207], v[16:19]
	v_mfma_f32_16x16x32_bf16 v[24:27], v[144:147], v[204:207], v[24:27]
	v_mfma_f32_16x16x32_bf16 v[24:27], v[140:143], v[200:203], v[24:27]
	s_barrier
	s_add_i32 s63, 0, 0x18000
	s_add_i32 s64, 0, 0x1c000
	v_add_u32_e32 v152, s63, v217
	v_add_u32_e32 v160, s64, v217
	ds_read_b128 v[140:143], v152
	ds_read_b128 v[144:147], v152 offset:1024
	ds_read_b128 v[148:151], v152 offset:2048
	ds_read_b128 v[152:155], v152 offset:3072
	ds_read_b128 v[156:159], v160
	ds_read_b128 v[164:167], v160 offset:1024
	ds_read_b128 v[168:171], v160 offset:2048
	ds_read_b128 v[172:175], v160 offset:3072
	s_add_u32 s30, s30, 0x4000
	s_addc_u32 s31, s31, 0
	s_mov_b32 m0, s40
	ds_read_b128 v[176:179], v222 offset:32768
	ds_read_b128 v[180:183], v222 offset:33792
	ds_read_b128 v[184:187], v222 offset:34816
	ds_read_b128 v[188:191], v222 offset:35840
	ds_read_b128 v[192:195], v222 offset:36864
	ds_read_b128 v[196:199], v222 offset:37888
	ds_read_b128 v[200:203], v222 offset:38912
	ds_read_b128 v[204:207], v222 offset:39936
	global_load_lds_dwordx4 v128, s[30:31]
	s_mov_b32 m0, s41
	s_nop 0
	global_load_lds_dwordx4 v130, s[30:31]
	s_waitcnt vmcnt(8)
	s_waitcnt lgkmcnt(0)
	s_barrier
	s_waitcnt lgkmcnt(0)
	v_mfma_f32_16x16x32_bf16 v[124:127], v[140:143], v[176:179], v[124:127]
	v_mfma_f32_16x16x32_bf16 v[124:127], v[144:147], v[180:183], v[124:127]
	v_mfma_f32_16x16x32_bf16 v[120:123], v[152:155], v[180:183], v[120:123]
	v_mfma_f32_16x16x32_bf16 v[120:123], v[148:151], v[176:179], v[120:123]
	v_mfma_f32_16x16x32_bf16 v[108:111], v[156:159], v[176:179], v[108:111]
	v_mfma_f32_16x16x32_bf16 v[108:111], v[164:167], v[180:183], v[108:111]
	v_mfma_f32_16x16x32_bf16 v[100:103], v[172:175], v[180:183], v[100:103]
	v_mfma_f32_16x16x32_bf16 v[100:103], v[168:171], v[176:179], v[100:103]
	v_mfma_f32_16x16x32_bf16 v[84:87], v[168:171], v[184:187], v[84:87]
	v_mfma_f32_16x16x32_bf16 v[84:87], v[172:175], v[188:191], v[84:87]
	v_mfma_f32_16x16x32_bf16 v[92:95], v[164:167], v[188:191], v[92:95]
	v_mfma_f32_16x16x32_bf16 v[92:95], v[156:159], v[184:187], v[92:95]
	v_mfma_f32_16x16x32_bf16 v[112:115], v[148:151], v[184:187], v[112:115]
	v_mfma_f32_16x16x32_bf16 v[112:115], v[152:155], v[188:191], v[112:115]
	v_mfma_f32_16x16x32_bf16 v[116:119], v[144:147], v[188:191], v[116:119]
	v_mfma_f32_16x16x32_bf16 v[116:119], v[140:143], v[184:187], v[116:119]
	v_mfma_f32_16x16x32_bf16 v[104:107], v[140:143], v[192:195], v[104:107]
	v_mfma_f32_16x16x32_bf16 v[104:107], v[144:147], v[196:199], v[104:107]
	v_mfma_f32_16x16x32_bf16 v[96:99], v[152:155], v[196:199], v[96:99]
	v_mfma_f32_16x16x32_bf16 v[96:99], v[148:151], v[192:195], v[96:99]
	v_mfma_f32_16x16x32_bf16 v[76:79], v[156:159], v[192:195], v[76:79]
	v_mfma_f32_16x16x32_bf16 v[76:79], v[164:167], v[196:199], v[76:79]
	v_mfma_f32_16x16x32_bf16 v[72:75], v[172:175], v[196:199], v[72:75]
	v_mfma_f32_16x16x32_bf16 v[72:75], v[168:171], v[192:195], v[72:75]
	v_mfma_f32_16x16x32_bf16 v[64:67], v[168:171], v[200:203], v[64:67]
	v_mfma_f32_16x16x32_bf16 v[64:67], v[172:175], v[204:207], v[64:67]
	v_mfma_f32_16x16x32_bf16 v[68:71], v[164:167], v[204:207], v[68:71]
	v_mfma_f32_16x16x32_bf16 v[68:71], v[156:159], v[200:203], v[68:71]
	v_mfma_f32_16x16x32_bf16 v[80:83], v[148:151], v[200:203], v[80:83]
	v_mfma_f32_16x16x32_bf16 v[80:83], v[152:155], v[204:207], v[80:83]
	v_mfma_f32_16x16x32_bf16 v[88:91], v[144:147], v[204:207], v[88:91]
	v_mfma_f32_16x16x32_bf16 v[88:91], v[140:143], v[200:203], v[88:91]
	s_barrier
	s_add_u32 s30, s28, 0x8000
	s_addc_u32 s31, s29, 0
	s_add_i32 s63, s63, s37
	s_mov_b32 m0, s63
	ds_read_b128 v[176:179], v222 offset:49152
	ds_read_b128 v[180:183], v222 offset:50176
	ds_read_b128 v[184:187], v222 offset:51200
	ds_read_b128 v[188:191], v222 offset:52224
	ds_read_b128 v[192:195], v222 offset:53248
	ds_read_b128 v[196:199], v222 offset:54272
	ds_read_b128 v[200:203], v222 offset:55296
	ds_read_b128 v[204:207], v222 offset:56320
	global_load_lds_dwordx4 v128, s[30:31]
	s_add_i32 m0, s63, 0x2000
	s_add_u32 s28, s28, 0xc000
	v_lshl_add_u64 v[160:161], s[30:31], 0, v[130:131]
	s_addc_u32 s29, s29, 0
	s_add_i32 s30, s64, s37
	global_load_lds_dwordx4 v[160:161], off
	s_mov_b32 m0, s30
	s_nop 0
	global_load_lds_dwordx4 v128, s[28:29]
	s_add_i32 m0, s30, 0x2000
	s_nop 0
	global_load_lds_dwordx4 v130, s[28:29]
	s_mov_b32 m0, s44
	s_nop 0
	global_load_lds_dwordx4 v128, s[26:27]
	s_mov_b32 m0, s45
	s_nop 0
	global_load_lds_dwordx4 v130, s[26:27]
	s_waitcnt vmcnt(8)
	s_waitcnt lgkmcnt(0)
	s_barrier
	s_waitcnt lgkmcnt(0)
	v_mfma_f32_16x16x32_bf16 v[60:63], v[140:143], v[176:179], v[60:63]
	v_mfma_f32_16x16x32_bf16 v[60:63], v[144:147], v[180:183], v[60:63]
	v_mfma_f32_16x16x32_bf16 v[56:59], v[152:155], v[180:183], v[56:59]
	v_mfma_f32_16x16x32_bf16 v[56:59], v[148:151], v[176:179], v[56:59]
	v_mfma_f32_16x16x32_bf16 v[44:47], v[156:159], v[176:179], v[44:47]
	v_mfma_f32_16x16x32_bf16 v[44:47], v[164:167], v[180:183], v[44:47]
	v_mfma_f32_16x16x32_bf16 v[36:39], v[172:175], v[180:183], v[36:39]
	v_mfma_f32_16x16x32_bf16 v[36:39], v[168:171], v[176:179], v[36:39]
	v_mfma_f32_16x16x32_bf16 v[20:23], v[168:171], v[184:187], v[20:23]
	v_mfma_f32_16x16x32_bf16 v[20:23], v[172:175], v[188:191], v[20:23]
	v_mfma_f32_16x16x32_bf16 v[28:31], v[164:167], v[188:191], v[28:31]
	v_mfma_f32_16x16x32_bf16 v[28:31], v[156:159], v[184:187], v[28:31]
	v_mfma_f32_16x16x32_bf16 v[48:51], v[148:151], v[184:187], v[48:51]
	v_mfma_f32_16x16x32_bf16 v[48:51], v[152:155], v[188:191], v[48:51]
	v_mfma_f32_16x16x32_bf16 v[52:55], v[144:147], v[188:191], v[52:55]
	v_mfma_f32_16x16x32_bf16 v[52:55], v[140:143], v[184:187], v[52:55]
	v_mfma_f32_16x16x32_bf16 v[40:43], v[140:143], v[192:195], v[40:43]
	v_mfma_f32_16x16x32_bf16 v[40:43], v[144:147], v[196:199], v[40:43]
	v_mfma_f32_16x16x32_bf16 v[32:35], v[152:155], v[196:199], v[32:35]
	v_mfma_f32_16x16x32_bf16 v[32:35], v[148:151], v[192:195], v[32:35]
	v_mfma_f32_16x16x32_bf16 v[12:15], v[156:159], v[192:195], v[12:15]
	v_mfma_f32_16x16x32_bf16 v[12:15], v[164:167], v[196:199], v[12:15]
	v_mfma_f32_16x16x32_bf16 v[8:11], v[172:175], v[196:199], v[8:11]
	v_mfma_f32_16x16x32_bf16 v[8:11], v[168:171], v[192:195], v[8:11]
	v_mfma_f32_16x16x32_bf16 v[0:3], v[168:171], v[200:203], v[0:3]
	v_mfma_f32_16x16x32_bf16 v[0:3], v[172:175], v[204:207], v[0:3]
	v_mfma_f32_16x16x32_bf16 v[4:7], v[164:167], v[204:207], v[4:7]
	v_mfma_f32_16x16x32_bf16 v[4:7], v[156:159], v[200:203], v[4:7]
	v_mfma_f32_16x16x32_bf16 v[16:19], v[148:151], v[200:203], v[16:19]
	v_mfma_f32_16x16x32_bf16 v[16:19], v[152:155], v[204:207], v[16:19]
	v_mfma_f32_16x16x32_bf16 v[24:27], v[144:147], v[204:207], v[24:27]
	v_mfma_f32_16x16x32_bf16 v[24:27], v[140:143], v[200:203], v[24:27]
	s_barrier
	s_add_u32 s24, s24, 0x10000
	s_addc_u32 s25, s25, 0
	s_add_u32 s60, s60, 0x10000
	s_addc_u32 s61, s61, 0
	s_cmp_ge_i32 s62, s43
	s_mov_b32 s26, s62
	s_cbranch_scc0 .LBB0_228
	v_pk_mul_f32 v[200:201], v[126:127], 0.5 op_sel_hi:[1,0]
	v_pk_mul_f32 v[202:203], v[124:125], 0.5 op_sel_hi:[1,0]
	v_pk_mul_f32 v[204:205], v[122:123], 0.5 op_sel_hi:[1,0]
	v_pk_mul_f32 v[206:207], v[120:121], 0.5 op_sel_hi:[1,0]
	v_pk_mul_f32 v[210:211], v[110:111], 0.5 op_sel_hi:[1,0]
	v_pk_mul_f32 v[208:209], v[108:109], 0.5 op_sel_hi:[1,0]
	v_pk_mul_f32 v[198:199], v[102:103], 0.5 op_sel_hi:[1,0]
	v_pk_mul_f32 v[196:197], v[100:101], 0.5 op_sel_hi:[1,0]
	v_pk_mul_f32 v[194:195], v[118:119], 0.5 op_sel_hi:[1,0]
	v_pk_mul_f32 v[192:193], v[116:117], 0.5 op_sel_hi:[1,0]
	v_pk_mul_f32 v[190:191], v[114:115], 0.5 op_sel_hi:[1,0]
	v_pk_mul_f32 v[188:189], v[112:113], 0.5 op_sel_hi:[1,0]
	v_pk_mul_f32 v[186:187], v[94:95], 0.5 op_sel_hi:[1,0]
	v_pk_mul_f32 v[184:185], v[92:93], 0.5 op_sel_hi:[1,0]
	v_pk_mul_f32 v[182:183], v[86:87], 0.5 op_sel_hi:[1,0]
	v_pk_mul_f32 v[180:181], v[84:85], 0.5 op_sel_hi:[1,0]
	v_pk_mul_f32 v[178:179], v[106:107], 0.5 op_sel_hi:[1,0]
	v_pk_mul_f32 v[176:177], v[104:105], 0.5 op_sel_hi:[1,0]
	v_pk_mul_f32 v[174:175], v[98:99], 0.5 op_sel_hi:[1,0]
	v_pk_mul_f32 v[172:173], v[96:97], 0.5 op_sel_hi:[1,0]
	v_pk_mul_f32 v[170:171], v[78:79], 0.5 op_sel_hi:[1,0]
	v_pk_mul_f32 v[168:169], v[76:77], 0.5 op_sel_hi:[1,0]
	v_pk_mul_f32 v[166:167], v[74:75], 0.5 op_sel_hi:[1,0]
	v_pk_mul_f32 v[164:165], v[72:73], 0.5 op_sel_hi:[1,0]
	v_pk_mul_f32 v[160:161], v[90:91], 0.5 op_sel_hi:[1,0]
	v_pk_mul_f32 v[158:159], v[88:89], 0.5 op_sel_hi:[1,0]
	v_pk_mul_f32 v[156:157], v[82:83], 0.5 op_sel_hi:[1,0]
	v_pk_mul_f32 v[154:155], v[80:81], 0.5 op_sel_hi:[1,0]
	v_pk_mul_f32 v[152:153], v[70:71], 0.5 op_sel_hi:[1,0]
	v_pk_mul_f32 v[150:151], v[68:69], 0.5 op_sel_hi:[1,0]
	v_pk_mul_f32 v[148:149], v[66:67], 0.5 op_sel_hi:[1,0]
	v_pk_mul_f32 v[146:147], v[64:65], 0.5 op_sel_hi:[1,0]
	v_pk_mul_f32 v[144:145], v[62:63], 0.5 op_sel_hi:[1,0]
	v_pk_mul_f32 v[142:143], v[60:61], 0.5 op_sel_hi:[1,0]
	v_pk_mul_f32 v[126:127], v[58:59], 0.5 op_sel_hi:[1,0]
	v_pk_mul_f32 v[124:125], v[56:57], 0.5 op_sel_hi:[1,0]
	v_pk_mul_f32 v[122:123], v[46:47], 0.5 op_sel_hi:[1,0]
	v_pk_mul_f32 v[120:121], v[44:45], 0.5 op_sel_hi:[1,0]
	v_pk_mul_f32 v[118:119], v[38:39], 0.5 op_sel_hi:[1,0]
	v_pk_mul_f32 v[116:117], v[36:37], 0.5 op_sel_hi:[1,0]
	v_pk_mul_f32 v[114:115], v[54:55], 0.5 op_sel_hi:[1,0]
	v_pk_mul_f32 v[112:113], v[52:53], 0.5 op_sel_hi:[1,0]
	v_pk_mul_f32 v[110:111], v[50:51], 0.5 op_sel_hi:[1,0]
	v_pk_mul_f32 v[108:109], v[48:49], 0.5 op_sel_hi:[1,0]
	v_pk_mul_f32 v[106:107], v[30:31], 0.5 op_sel_hi:[1,0]
	v_pk_mul_f32 v[104:105], v[28:29], 0.5 op_sel_hi:[1,0]
	v_pk_mul_f32 v[102:103], v[22:23], 0.5 op_sel_hi:[1,0]
	v_pk_mul_f32 v[100:101], v[20:21], 0.5 op_sel_hi:[1,0]
	v_pk_mul_f32 v[98:99], v[42:43], 0.5 op_sel_hi:[1,0]
	v_pk_mul_f32 v[96:97], v[40:41], 0.5 op_sel_hi:[1,0]
	v_pk_mul_f32 v[94:95], v[34:35], 0.5 op_sel_hi:[1,0]
	v_pk_mul_f32 v[92:93], v[32:33], 0.5 op_sel_hi:[1,0]
	v_pk_mul_f32 v[90:91], v[14:15], 0.5 op_sel_hi:[1,0]
	v_pk_mul_f32 v[88:89], v[12:13], 0.5 op_sel_hi:[1,0]
	v_pk_mul_f32 v[86:87], v[10:11], 0.5 op_sel_hi:[1,0]
	v_pk_mul_f32 v[84:85], v[8:9], 0.5 op_sel_hi:[1,0]
	v_pk_mul_f32 v[82:83], v[26:27], 0.5 op_sel_hi:[1,0]
	v_pk_mul_f32 v[80:81], v[24:25], 0.5 op_sel_hi:[1,0]
	v_pk_mul_f32 v[78:79], v[18:19], 0.5 op_sel_hi:[1,0]
	v_pk_mul_f32 v[76:77], v[16:17], 0.5 op_sel_hi:[1,0]
	v_pk_mul_f32 v[74:75], v[6:7], 0.5 op_sel_hi:[1,0]
	v_pk_mul_f32 v[72:73], v[4:5], 0.5 op_sel_hi:[1,0]
	v_pk_mul_f32 v[70:71], v[2:3], 0.5 op_sel_hi:[1,0]
	v_pk_mul_f32 v[68:69], v[0:1], 0.5 op_sel_hi:[1,0]

.LBB0_1056:
	ds_read_b128 v[140:143], v222
	ds_read_b128 v[144:147], v222 offset:1024
	ds_read_b128 v[148:151], v222 offset:2048
	ds_read_b128 v[152:155], v222 offset:3072
	ds_read_b128 v[156:159], v223
	ds_read_b128 v[160:163], v223 offset:1024
	ds_read_b128 v[164:167], v223 offset:2048
	ds_read_b128 v[168:171], v223 offset:3072
	s_add_i32 s62, s26, 2
	s_add_u32 s27, s24, 0x4000
	s_addc_u32 s28, s25, 0
	s_cmp_eq_u32 s46, s26
	s_cselect_b32 s30, s0, s27
	s_cselect_b32 s31, s1, s28
	s_cselect_b32 s28, s22, s60
	s_cselect_b32 s29, s23, s61
	s_add_u32 s26, s30, 0x8000
	s_addc_u32 s27, s31, 0
	s_add_i32 m0, s38, 0xc000
	ds_read_b128 v[172:175], v224
	ds_read_b128 v[176:179], v224 offset:1024
	ds_read_b128 v[180:183], v224 offset:2048
	ds_read_b128 v[184:187], v224 offset:3072
	ds_read_b128 v[188:191], v224 offset:4096
	ds_read_b128 v[192:195], v224 offset:5120
	ds_read_b128 v[196:199], v224 offset:6144
	ds_read_b128 v[200:203], v224 offset:7168
	global_load_lds_dwordx4 v132, s[24:25]
	s_add_i32 m0, s38, 0xe000
	s_nop 0
	global_load_lds_dwordx4 v134, s[24:25]
	s_waitcnt vmcnt(8)
	s_waitcnt lgkmcnt(0)
	s_barrier
	s_waitcnt lgkmcnt(0)
	v_mfma_f32_16x16x32_bf16 v[124:127], v[140:143], v[172:175], v[124:127]
	v_mfma_f32_16x16x32_bf16 v[124:127], v[144:147], v[176:179], v[124:127]
	v_mfma_f32_16x16x32_bf16 v[120:123], v[152:155], v[176:179], v[120:123]
	v_mfma_f32_16x16x32_bf16 v[120:123], v[148:151], v[172:175], v[120:123]
	v_mfma_f32_16x16x32_bf16 v[108:111], v[156:159], v[172:175], v[108:111]
	v_mfma_f32_16x16x32_bf16 v[108:111], v[160:163], v[176:179], v[108:111]
	v_mfma_f32_16x16x32_bf16 v[100:103], v[168:171], v[176:179], v[100:103]
	v_mfma_f32_16x16x32_bf16 v[100:103], v[164:167], v[172:175], v[100:103]
	v_mfma_f32_16x16x32_bf16 v[84:87], v[164:167], v[180:183], v[84:87]
	v_mfma_f32_16x16x32_bf16 v[84:87], v[168:171], v[184:187], v[84:87]
	v_mfma_f32_16x16x32_bf16 v[92:95], v[160:163], v[184:187], v[92:95]
	v_mfma_f32_16x16x32_bf16 v[92:95], v[156:159], v[180:183], v[92:95]
	v_mfma_f32_16x16x32_bf16 v[112:115], v[148:151], v[180:183], v[112:115]
	v_mfma_f32_16x16x32_bf16 v[112:115], v[152:155], v[184:187], v[112:115]
	v_mfma_f32_16x16x32_bf16 v[116:119], v[144:147], v[184:187], v[116:119]
	v_mfma_f32_16x16x32_bf16 v[116:119], v[140:143], v[180:183], v[116:119]
	v_mfma_f32_16x16x32_bf16 v[104:107], v[140:143], v[188:191], v[104:107]
	v_mfma_f32_16x16x32_bf16 v[104:107], v[144:147], v[192:195], v[104:107]
	v_mfma_f32_16x16x32_bf16 v[96:99], v[152:155], v[192:195], v[96:99]
	v_mfma_f32_16x16x32_bf16 v[96:99], v[148:151], v[188:191], v[96:99]
	v_mfma_f32_16x16x32_bf16 v[76:79], v[156:159], v[188:191], v[76:79]
	v_mfma_f32_16x16x32_bf16 v[76:79], v[160:163], v[192:195], v[76:79]
	v_mfma_f32_16x16x32_bf16 v[72:75], v[168:171], v[192:195], v[72:75]
	v_mfma_f32_16x16x32_bf16 v[72:75], v[164:167], v[188:191], v[72:75]
	v_mfma_f32_16x16x32_bf16 v[64:67], v[164:167], v[196:199], v[64:67]
	v_mfma_f32_16x16x32_bf16 v[64:67], v[168:171], v[200:203], v[64:67]
	v_mfma_f32_16x16x32_bf16 v[68:71], v[160:163], v[200:203], v[68:71]
	v_mfma_f32_16x16x32_bf16 v[68:71], v[156:159], v[196:199], v[68:71]
	v_mfma_f32_16x16x32_bf16 v[80:83], v[148:151], v[196:199], v[80:83]
	v_mfma_f32_16x16x32_bf16 v[80:83], v[152:155], v[200:203], v[80:83]
	v_mfma_f32_16x16x32_bf16 v[88:91], v[144:147], v[200:203], v[88:91]
	v_mfma_f32_16x16x32_bf16 v[88:91], v[140:143], v[196:199], v[88:91]
	s_barrier
	s_add_i32 s63, s50, s37
	s_mov_b32 m0, s63
	ds_read_b128 v[172:175], v224 offset:16384
	ds_read_b128 v[176:179], v224 offset:17408
	ds_read_b128 v[180:183], v224 offset:18432
	ds_read_b128 v[184:187], v224 offset:19456
	ds_read_b128 v[188:191], v224 offset:20480
	ds_read_b128 v[192:195], v224 offset:21504
	ds_read_b128 v[196:199], v224 offset:22528
	ds_read_b128 v[200:203], v224 offset:23552
	global_load_lds_dwordx4 v128, s[28:29]
	s_add_i32 m0, s63, 0x2000
	s_add_u32 s64, s28, 0x4000
	s_addc_u32 s65, s29, 0
	s_add_i32 s63, s51, s37
	global_load_lds_dwordx4 v130, s[28:29]
	s_mov_b32 m0, s63
	s_nop 0
	global_load_lds_dwordx4 v128, s[64:65]
	s_add_i32 m0, s63, 0x2000
	s_nop 0
	global_load_lds_dwordx4 v130, s[64:65]
	s_mov_b32 m0, s38
	s_nop 0
	global_load_lds_dwordx4 v128, s[30:31]
	s_mov_b32 m0, s39
	s_nop 0
	global_load_lds_dwordx4 v130, s[30:31]
	s_waitcnt vmcnt(8)
	s_waitcnt lgkmcnt(0)
	s_barrier
	s_waitcnt lgkmcnt(0)
	v_mfma_f32_16x16x32_bf16 v[60:63], v[140:143], v[172:175], v[60:63]
	v_mfma_f32_16x16x32_bf16 v[60:63], v[144:147], v[176:179], v[60:63]
	v_mfma_f32_16x16x32_bf16 v[56:59], v[152:155], v[176:179], v[56:59]
	v_mfma_f32_16x16x32_bf16 v[56:59], v[148:151], v[172:175], v[56:59]
	v_mfma_f32_16x16x32_bf16 v[44:47], v[156:159], v[172:175], v[44:47]
	v_mfma_f32_16x16x32_bf16 v[44:47], v[160:163], v[176:179], v[44:47]
	v_mfma_f32_16x16x32_bf16 v[36:39], v[168:171], v[176:179], v[36:39]
	v_mfma_f32_16x16x32_bf16 v[36:39], v[164:167], v[172:175], v[36:39]
	v_mfma_f32_16x16x32_bf16 v[20:23], v[164:167], v[180:183], v[20:23]
	v_mfma_f32_16x16x32_bf16 v[20:23], v[168:171], v[184:187], v[20:23]
	v_mfma_f32_16x16x32_bf16 v[28:31], v[160:163], v[184:187], v[28:31]
	v_mfma_f32_16x16x32_bf16 v[28:31], v[156:159], v[180:183], v[28:31]
	v_mfma_f32_16x16x32_bf16 v[48:51], v[148:151], v[180:183], v[48:51]
	v_mfma_f32_16x16x32_bf16 v[48:51], v[152:155], v[184:187], v[48:51]
	v_mfma_f32_16x16x32_bf16 v[52:55], v[144:147], v[184:187], v[52:55]
	v_mfma_f32_16x16x32_bf16 v[52:55], v[140:143], v[180:183], v[52:55]
	v_mfma_f32_16x16x32_bf16 v[40:43], v[140:143], v[188:191], v[40:43]
	v_mfma_f32_16x16x32_bf16 v[40:43], v[144:147], v[192:195], v[40:43]
	v_mfma_f32_16x16x32_bf16 v[32:35], v[152:155], v[192:195], v[32:35]
	v_mfma_f32_16x16x32_bf16 v[32:35], v[148:151], v[188:191], v[32:35]
	v_mfma_f32_16x16x32_bf16 v[12:15], v[156:159], v[188:191], v[12:15]
	v_mfma_f32_16x16x32_bf16 v[12:15], v[160:163], v[192:195], v[12:15]
	v_mfma_f32_16x16x32_bf16 v[8:11], v[168:171], v[192:195], v[8:11]
	v_mfma_f32_16x16x32_bf16 v[8:11], v[164:167], v[188:191], v[8:11]
	v_mfma_f32_16x16x32_bf16 v[0:3], v[164:167], v[196:199], v[0:3]
	v_mfma_f32_16x16x32_bf16 v[0:3], v[168:171], v[200:203], v[0:3]
	v_mfma_f32_16x16x32_bf16 v[4:7], v[160:163], v[200:203], v[4:7]
	v_mfma_f32_16x16x32_bf16 v[4:7], v[156:159], v[196:199], v[4:7]
	v_mfma_f32_16x16x32_bf16 v[16:19], v[148:151], v[196:199], v[16:19]
	v_mfma_f32_16x16x32_bf16 v[16:19], v[152:155], v[200:203], v[16:19]
	v_mfma_f32_16x16x32_bf16 v[24:27], v[144:147], v[200:203], v[24:27]
	v_mfma_f32_16x16x32_bf16 v[24:27], v[140:143], v[196:199], v[24:27]
	s_barrier
	s_add_i32 s63, 0, 0x18000
	s_add_i32 s64, 0, 0x1c000
	v_add_u32_e32 v152, s63, v219
	v_add_u32_e32 v168, s64, v219
	ds_read_b128 v[140:143], v152
	ds_read_b128 v[144:147], v152 offset:1024
	ds_read_b128 v[148:151], v152 offset:2048
	ds_read_b128 v[152:155], v152 offset:3072
	ds_read_b128 v[156:159], v168
	ds_read_b128 v[160:163], v168 offset:1024
	ds_read_b128 v[164:167], v168 offset:2048
	ds_read_b128 v[168:171], v168 offset:3072
	s_add_u32 s30, s30, 0x4000
	s_addc_u32 s31, s31, 0
	s_mov_b32 m0, s40
	ds_read_b128 v[172:175], v224 offset:32768
	ds_read_b128 v[176:179], v224 offset:33792
	ds_read_b128 v[180:183], v224 offset:34816
	ds_read_b128 v[184:187], v224 offset:35840
	ds_read_b128 v[188:191], v224 offset:36864
	ds_read_b128 v[192:195], v224 offset:37888
	ds_read_b128 v[196:199], v224 offset:38912
	ds_read_b128 v[200:203], v224 offset:39936
	global_load_lds_dwordx4 v128, s[30:31]
	s_mov_b32 m0, s41
	s_nop 0
	global_load_lds_dwordx4 v130, s[30:31]
	s_waitcnt vmcnt(8)
	s_waitcnt lgkmcnt(0)
	s_barrier
	s_waitcnt lgkmcnt(0)
	v_mfma_f32_16x16x32_bf16 v[124:127], v[140:143], v[172:175], v[124:127]
	v_mfma_f32_16x16x32_bf16 v[124:127], v[144:147], v[176:179], v[124:127]
	v_mfma_f32_16x16x32_bf16 v[120:123], v[152:155], v[176:179], v[120:123]
	v_mfma_f32_16x16x32_bf16 v[120:123], v[148:151], v[172:175], v[120:123]
	v_mfma_f32_16x16x32_bf16 v[108:111], v[156:159], v[172:175], v[108:111]
	v_mfma_f32_16x16x32_bf16 v[108:111], v[160:163], v[176:179], v[108:111]
	v_mfma_f32_16x16x32_bf16 v[100:103], v[168:171], v[176:179], v[100:103]
	v_mfma_f32_16x16x32_bf16 v[100:103], v[164:167], v[172:175], v[100:103]
	v_mfma_f32_16x16x32_bf16 v[84:87], v[164:167], v[180:183], v[84:87]
	v_mfma_f32_16x16x32_bf16 v[84:87], v[168:171], v[184:187], v[84:87]
	v_mfma_f32_16x16x32_bf16 v[92:95], v[160:163], v[184:187], v[92:95]
	v_mfma_f32_16x16x32_bf16 v[92:95], v[156:159], v[180:183], v[92:95]
	v_mfma_f32_16x16x32_bf16 v[112:115], v[148:151], v[180:183], v[112:115]
	v_mfma_f32_16x16x32_bf16 v[112:115], v[152:155], v[184:187], v[112:115]
	v_mfma_f32_16x16x32_bf16 v[116:119], v[144:147], v[184:187], v[116:119]
	v_mfma_f32_16x16x32_bf16 v[116:119], v[140:143], v[180:183], v[116:119]
	v_mfma_f32_16x16x32_bf16 v[104:107], v[140:143], v[188:191], v[104:107]
	v_mfma_f32_16x16x32_bf16 v[104:107], v[144:147], v[192:195], v[104:107]
	v_mfma_f32_16x16x32_bf16 v[96:99], v[152:155], v[192:195], v[96:99]
	v_mfma_f32_16x16x32_bf16 v[96:99], v[148:151], v[188:191], v[96:99]
	v_mfma_f32_16x16x32_bf16 v[76:79], v[156:159], v[188:191], v[76:79]
	v_mfma_f32_16x16x32_bf16 v[76:79], v[160:163], v[192:195], v[76:79]
	v_mfma_f32_16x16x32_bf16 v[72:75], v[168:171], v[192:195], v[72:75]
	v_mfma_f32_16x16x32_bf16 v[72:75], v[164:167], v[188:191], v[72:75]
	v_mfma_f32_16x16x32_bf16 v[64:67], v[164:167], v[196:199], v[64:67]
	v_mfma_f32_16x16x32_bf16 v[64:67], v[168:171], v[200:203], v[64:67]
	v_mfma_f32_16x16x32_bf16 v[68:71], v[160:163], v[200:203], v[68:71]
	v_mfma_f32_16x16x32_bf16 v[68:71], v[156:159], v[196:199], v[68:71]
	v_mfma_f32_16x16x32_bf16 v[80:83], v[148:151], v[196:199], v[80:83]
	v_mfma_f32_16x16x32_bf16 v[80:83], v[152:155], v[200:203], v[80:83]
	v_mfma_f32_16x16x32_bf16 v[88:91], v[144:147], v[200:203], v[88:91]
	v_mfma_f32_16x16x32_bf16 v[88:91], v[140:143], v[196:199], v[88:91]
	s_barrier
	s_add_u32 s30, s28, 0x8000
	s_addc_u32 s31, s29, 0
	s_add_i32 s63, s63, s37
	s_mov_b32 m0, s63
	ds_read_b128 v[172:175], v224 offset:49152
	ds_read_b128 v[176:179], v224 offset:50176
	ds_read_b128 v[180:183], v224 offset:51200
	ds_read_b128 v[184:187], v224 offset:52224
	ds_read_b128 v[188:191], v224 offset:53248
	ds_read_b128 v[192:195], v224 offset:54272
	ds_read_b128 v[196:199], v224 offset:55296
	ds_read_b128 v[200:203], v224 offset:56320
	global_load_lds_dwordx4 v128, s[30:31]
	s_add_i32 m0, s63, 0x2000
	s_add_u32 s28, s28, 0xc000
	v_lshl_add_u64 v[204:205], s[30:31], 0, v[130:131]
	s_addc_u32 s29, s29, 0
	s_add_i32 s30, s64, s37
	global_load_lds_dwordx4 v[204:205], off
	s_mov_b32 m0, s30
	s_nop 0
	global_load_lds_dwordx4 v128, s[28:29]
	s_add_i32 m0, s30, 0x2000
	s_nop 0
	global_load_lds_dwordx4 v130, s[28:29]
	s_mov_b32 m0, s44
	s_nop 0
	global_load_lds_dwordx4 v128, s[26:27]
	s_mov_b32 m0, s45
	s_nop 0
	global_load_lds_dwordx4 v130, s[26:27]
	s_waitcnt vmcnt(8)
	s_waitcnt lgkmcnt(0)
	s_barrier
	s_waitcnt lgkmcnt(0)
	v_mfma_f32_16x16x32_bf16 v[60:63], v[140:143], v[172:175], v[60:63]
	v_mfma_f32_16x16x32_bf16 v[60:63], v[144:147], v[176:179], v[60:63]
	v_mfma_f32_16x16x32_bf16 v[56:59], v[152:155], v[176:179], v[56:59]
	v_mfma_f32_16x16x32_bf16 v[56:59], v[148:151], v[172:175], v[56:59]
	v_mfma_f32_16x16x32_bf16 v[44:47], v[156:159], v[172:175], v[44:47]
	v_mfma_f32_16x16x32_bf16 v[44:47], v[160:163], v[176:179], v[44:47]
	v_mfma_f32_16x16x32_bf16 v[36:39], v[168:171], v[176:179], v[36:39]
	v_mfma_f32_16x16x32_bf16 v[36:39], v[164:167], v[172:175], v[36:39]
	v_mfma_f32_16x16x32_bf16 v[20:23], v[164:167], v[180:183], v[20:23]
	v_mfma_f32_16x16x32_bf16 v[20:23], v[168:171], v[184:187], v[20:23]
	v_mfma_f32_16x16x32_bf16 v[28:31], v[160:163], v[184:187], v[28:31]
	v_mfma_f32_16x16x32_bf16 v[28:31], v[156:159], v[180:183], v[28:31]
	v_mfma_f32_16x16x32_bf16 v[48:51], v[148:151], v[180:183], v[48:51]
	v_mfma_f32_16x16x32_bf16 v[48:51], v[152:155], v[184:187], v[48:51]
	v_mfma_f32_16x16x32_bf16 v[52:55], v[144:147], v[184:187], v[52:55]
	v_mfma_f32_16x16x32_bf16 v[52:55], v[140:143], v[180:183], v[52:55]
	v_mfma_f32_16x16x32_bf16 v[40:43], v[140:143], v[188:191], v[40:43]
	v_mfma_f32_16x16x32_bf16 v[40:43], v[144:147], v[192:195], v[40:43]
	v_mfma_f32_16x16x32_bf16 v[32:35], v[152:155], v[192:195], v[32:35]
	v_mfma_f32_16x16x32_bf16 v[32:35], v[148:151], v[188:191], v[32:35]
	v_mfma_f32_16x16x32_bf16 v[12:15], v[156:159], v[188:191], v[12:15]
	v_mfma_f32_16x16x32_bf16 v[12:15], v[160:163], v[192:195], v[12:15]
	v_mfma_f32_16x16x32_bf16 v[8:11], v[168:171], v[192:195], v[8:11]
	v_mfma_f32_16x16x32_bf16 v[8:11], v[164:167], v[188:191], v[8:11]
	v_mfma_f32_16x16x32_bf16 v[0:3], v[164:167], v[196:199], v[0:3]
	v_mfma_f32_16x16x32_bf16 v[0:3], v[168:171], v[200:203], v[0:3]
	v_mfma_f32_16x16x32_bf16 v[4:7], v[160:163], v[200:203], v[4:7]
	v_mfma_f32_16x16x32_bf16 v[4:7], v[156:159], v[196:199], v[4:7]
	v_mfma_f32_16x16x32_bf16 v[16:19], v[148:151], v[196:199], v[16:19]
	v_mfma_f32_16x16x32_bf16 v[16:19], v[152:155], v[200:203], v[16:19]
	v_mfma_f32_16x16x32_bf16 v[24:27], v[144:147], v[200:203], v[24:27]
	v_mfma_f32_16x16x32_bf16 v[24:27], v[140:143], v[196:199], v[24:27]
	s_barrier
	s_add_u32 s24, s24, 0x10000
	s_addc_u32 s25, s25, 0
	s_add_u32 s60, s60, 0x10000
	s_addc_u32 s61, s61, 0
	s_cmp_ge_i32 s62, s43
	s_mov_b32 s26, s62
	s_cbranch_scc0 .LBB0_1056
	v_pk_mul_f32 v[198:199], v[126:127], 0.5 op_sel_hi:[1,0]
	v_pk_mul_f32 v[200:201], v[124:125], 0.5 op_sel_hi:[1,0]
	v_pk_mul_f32 v[202:203], v[122:123], 0.5 op_sel_hi:[1,0]
	v_pk_mul_f32 v[204:205], v[120:121], 0.5 op_sel_hi:[1,0]
	v_pk_mul_f32 v[208:209], v[110:111], 0.5 op_sel_hi:[1,0]
	v_pk_mul_f32 v[206:207], v[108:109], 0.5 op_sel_hi:[1,0]
	v_pk_mul_f32 v[196:197], v[102:103], 0.5 op_sel_hi:[1,0]
	v_pk_mul_f32 v[194:195], v[100:101], 0.5 op_sel_hi:[1,0]
	v_pk_mul_f32 v[192:193], v[118:119], 0.5 op_sel_hi:[1,0]
	v_pk_mul_f32 v[190:191], v[116:117], 0.5 op_sel_hi:[1,0]
	v_pk_mul_f32 v[188:189], v[114:115], 0.5 op_sel_hi:[1,0]
	v_pk_mul_f32 v[186:187], v[112:113], 0.5 op_sel_hi:[1,0]
	v_pk_mul_f32 v[184:185], v[94:95], 0.5 op_sel_hi:[1,0]
	v_pk_mul_f32 v[182:183], v[92:93], 0.5 op_sel_hi:[1,0]
	v_pk_mul_f32 v[180:181], v[86:87], 0.5 op_sel_hi:[1,0]
	v_pk_mul_f32 v[178:179], v[84:85], 0.5 op_sel_hi:[1,0]
	v_pk_mul_f32 v[176:177], v[106:107], 0.5 op_sel_hi:[1,0]
	v_pk_mul_f32 v[174:175], v[104:105], 0.5 op_sel_hi:[1,0]
	v_pk_mul_f32 v[172:173], v[98:99], 0.5 op_sel_hi:[1,0]
	v_pk_mul_f32 v[170:171], v[96:97], 0.5 op_sel_hi:[1,0]
	v_pk_mul_f32 v[168:169], v[78:79], 0.5 op_sel_hi:[1,0]
	v_pk_mul_f32 v[166:167], v[76:77], 0.5 op_sel_hi:[1,0]
	v_pk_mul_f32 v[164:165], v[74:75], 0.5 op_sel_hi:[1,0]
	v_pk_mul_f32 v[162:163], v[72:73], 0.5 op_sel_hi:[1,0]
	v_pk_mul_f32 v[160:161], v[90:91], 0.5 op_sel_hi:[1,0]
	v_pk_mul_f32 v[158:159], v[88:89], 0.5 op_sel_hi:[1,0]
	v_pk_mul_f32 v[156:157], v[82:83], 0.5 op_sel_hi:[1,0]
	v_pk_mul_f32 v[154:155], v[80:81], 0.5 op_sel_hi:[1,0]
	v_pk_mul_f32 v[152:153], v[70:71], 0.5 op_sel_hi:[1,0]
	v_pk_mul_f32 v[150:151], v[68:69], 0.5 op_sel_hi:[1,0]
	v_pk_mul_f32 v[148:149], v[66:67], 0.5 op_sel_hi:[1,0]
	v_pk_mul_f32 v[146:147], v[64:65], 0.5 op_sel_hi:[1,0]
	v_pk_mul_f32 v[142:143], v[62:63], 0.5 op_sel_hi:[1,0]
	v_pk_mul_f32 v[140:141], v[60:61], 0.5 op_sel_hi:[1,0]
	v_pk_mul_f32 v[126:127], v[58:59], 0.5 op_sel_hi:[1,0]
	v_pk_mul_f32 v[124:125], v[56:57], 0.5 op_sel_hi:[1,0]
	v_pk_mul_f32 v[122:123], v[46:47], 0.5 op_sel_hi:[1,0]
	v_pk_mul_f32 v[120:121], v[44:45], 0.5 op_sel_hi:[1,0]
	v_pk_mul_f32 v[118:119], v[38:39], 0.5 op_sel_hi:[1,0]
	v_pk_mul_f32 v[116:117], v[36:37], 0.5 op_sel_hi:[1,0]
	v_pk_mul_f32 v[114:115], v[54:55], 0.5 op_sel_hi:[1,0]
	v_pk_mul_f32 v[112:113], v[52:53], 0.5 op_sel_hi:[1,0]
	v_pk_mul_f32 v[110:111], v[50:51], 0.5 op_sel_hi:[1,0]
	v_pk_mul_f32 v[108:109], v[48:49], 0.5 op_sel_hi:[1,0]
	v_pk_mul_f32 v[106:107], v[30:31], 0.5 op_sel_hi:[1,0]
	v_pk_mul_f32 v[104:105], v[28:29], 0.5 op_sel_hi:[1,0]
	v_pk_mul_f32 v[102:103], v[22:23], 0.5 op_sel_hi:[1,0]
	v_pk_mul_f32 v[100:101], v[20:21], 0.5 op_sel_hi:[1,0]
	v_pk_mul_f32 v[98:99], v[42:43], 0.5 op_sel_hi:[1,0]
	v_pk_mul_f32 v[96:97], v[40:41], 0.5 op_sel_hi:[1,0]
	v_pk_mul_f32 v[94:95], v[34:35], 0.5 op_sel_hi:[1,0]
	v_pk_mul_f32 v[92:93], v[32:33], 0.5 op_sel_hi:[1,0]
	v_pk_mul_f32 v[90:91], v[14:15], 0.5 op_sel_hi:[1,0]
	v_pk_mul_f32 v[88:89], v[12:13], 0.5 op_sel_hi:[1,0]
	v_pk_mul_f32 v[86:87], v[10:11], 0.5 op_sel_hi:[1,0]
	v_pk_mul_f32 v[84:85], v[8:9], 0.5 op_sel_hi:[1,0]
	v_pk_mul_f32 v[82:83], v[26:27], 0.5 op_sel_hi:[1,0]
	v_pk_mul_f32 v[80:81], v[24:25], 0.5 op_sel_hi:[1,0]
	v_pk_mul_f32 v[78:79], v[18:19], 0.5 op_sel_hi:[1,0]
	v_pk_mul_f32 v[76:77], v[16:17], 0.5 op_sel_hi:[1,0]
	v_pk_mul_f32 v[74:75], v[6:7], 0.5 op_sel_hi:[1,0]
	v_pk_mul_f32 v[72:73], v[4:5], 0.5 op_sel_hi:[1,0]
	v_pk_mul_f32 v[70:71], v[2:3], 0.5 op_sel_hi:[1,0]
	v_pk_mul_f32 v[68:69], v[0:1], 0.5 op_sel_hi:[1,0]
